# fused final epilogue: row-panel completion counter bumped once per workgroup (wave 0 after a workgroup barrier) instead of once per wave
# speedup vs baseline: 1.0076x; 1.0008x over previous
.LBB0_1504:
	s_or_b64 exec, exec, s[0:1]
	s_lshl_b32 s0, s10, 6
	s_ashr_i32 s1, s0, 31
	s_lshl_b64 s[0:1], s[0:1], 2
	s_add_u32 s0, s74, s0
	s_waitcnt vmcnt(0)
	s_addc_u32 s1, s75, s1
	s_add_u32 s0, s0, 0x8000
	s_addc_u32 s1, s1, 0
	s_barrier
	v_readfirstlane_b32 s2, v206
	s_cmp_lt_u32 s2, 64
	s_cbranch_scc0 .Lfin_wait
	v_cmp_eq_u32_e32 vcc, 0, v209
	s_and_saveexec_b64 s[4:5], vcc
	s_cbranch_execz .LBB0_1507
	s_mov_b64 s[8:9], exec
	v_mbcnt_lo_u32_b32 v0, s8, 0
	v_mbcnt_hi_u32_b32 v0, s9, v0
	v_cmp_eq_u32_e32 vcc, 0, v0
	s_and_b64 s[2:3], exec, vcc
	s_mov_b64 exec, s[2:3]
	s_cbranch_execz .LBB0_1507
	s_bcnt1_i32_b64 s2, s[8:9]
	v_mov_b32_e32 v0, 0
	s_waitcnt lgkmcnt(0)
	v_mov_b32_e32 v1, s2
	global_atomic_add v0, v1, s[0:1]

.LBB0_1509:
	s_waitcnt lgkmcnt(0)
	global_load_dword v1, v0, s[0:1] sc1
	s_mov_b64 s[4:5], -1
	s_waitcnt vmcnt(0)
	v_readfirstlane_b32 s3, v1
	s_cmp_gt_u32 s3, 3
	s_cbranch_scc1 .LBB0_1508
	s_sleep 2
	global_load_dword v1, v0, s[0:1] sc1
	s_waitcnt vmcnt(0)
	v_readfirstlane_b32 s3, v1
	s_cmp_lt_u32 s3, 4
	s_cbranch_scc0 .LBB0_1508
	s_sleep 2
	global_load_dword v1, v0, s[0:1] sc1
	s_waitcnt vmcnt(0)
	v_readfirstlane_b32 s3, v1
	s_cmp_lt_u32 s3, 4
	s_cbranch_scc0 .LBB0_1508
	s_sleep 2
	global_load_dword v1, v0, s[0:1] sc1
	s_waitcnt vmcnt(0)
	v_readfirstlane_b32 s3, v1
	s_cmp_lt_u32 s3, 4
	s_cbranch_scc0 .LBB0_1508
	s_sleep 2
	global_load_dword v1, v0, s[0:1] sc1
	s_waitcnt vmcnt(0)
	v_readfirstlane_b32 s3, v1
	s_cmp_lt_u32 s3, 4
	s_cbranch_scc0 .LBB0_1508
	s_add_i32 s2, s2, -5
	s_cmp_eq_u32 s2, 0
	s_cselect_b64 s[4:5], -1, 0
	s_sleep 2
	s_branch .LBB0_1508
.LBB0_1515:
.Lfin_wait:
	s_barrier
	v_lshlrev_b64 v[74:75], 2, v[184:185]
	v_lshl_add_u64 v[0:1], s[46:47], 0, v[74:75]
	global_load_dwordx4 v[12:15], v[0:1], off
	global_load_dwordx4 v[8:11], v[0:1], off offset:64
	global_load_dwordx4 v[4:7], v[0:1], off offset:512
	s_nop 0
	global_load_dwordx4 v[0:3], v[0:1], off offset:576
	s_nop 0
	global_load_dword v88, v[186:187], off sc1
	global_load_dword v89, v[186:187], off offset:64 sc1
	global_load_dword v90, v[186:187], off offset:128 sc1
	global_load_dword v91, v[186:187], off offset:192 sc1
	v_lshl_add_u64 v[78:79], s[72:73], 0, v[182:183]
	v_lshl_add_u64 v[82:83], s[72:73], 0, v[180:181]
	global_load_dword v181, v[186:187], off offset:512 sc1
	global_load_dword v182, v[186:187], off offset:576 sc1
	global_load_dword v183, v[186:187], off offset:640 sc1
	global_load_dword v185, v[186:187], off offset:704 sc1
	v_mov_b32_e32 v184, 0x358637bd
	v_lshl_add_u64 v[86:87], s[72:73], 0, v[178:179]
	v_lshl_add_u64 v[178:179], v[86:87], 0, v[74:75]
	v_lshl_add_u64 v[78:79], v[78:79], 0, v[74:75]
	v_lshl_add_u64 v[82:83], v[82:83], 0, v[74:75]
	s_waitcnt vmcnt(7)
	v_fmamk_f32 v86, v88, 0x3a800000, v184
	s_waitcnt vmcnt(6)
	v_fmamk_f32 v87, v89, 0x3a800000, v184
	s_waitcnt vmcnt(5)
	v_fmamk_f32 v89, v90, 0x3a800000, v184
	v_rsq_f32_e32 v86, v86
	s_waitcnt vmcnt(4)
	v_fmamk_f32 v91, v91, 0x3a800000, v184
	v_rsq_f32_e32 v88, v87
	v_rsq_f32_e32 v90, v89
	v_rsq_f32_e32 v180, v91
	v_pk_mul_f32 v[92:93], v[124:125], v[86:87] op_sel_hi:[1,0]
	v_pk_mul_f32 v[94:95], v[126:127], v[86:87] op_sel_hi:[1,0]
	v_pk_mul_f32 v[96:97], v[120:121], v[86:87] op_sel_hi:[1,0]
	v_pk_mul_f32 v[98:99], v[122:123], v[86:87] op_sel_hi:[1,0]
	v_pk_mul_f32 v[100:101], v[116:117], v[86:87] op_sel_hi:[1,0]
	v_pk_mul_f32 v[102:103], v[118:119], v[86:87] op_sel_hi:[1,0]
	v_pk_mul_f32 v[104:105], v[112:113], v[86:87] op_sel_hi:[1,0]
	v_pk_mul_f32 v[106:107], v[114:115], v[86:87] op_sel_hi:[1,0]
	v_pk_mul_f32 v[108:109], v[172:173], v[88:89] op_sel_hi:[1,0]
	v_pk_mul_f32 v[110:111], v[174:175], v[88:89] op_sel_hi:[1,0]
	v_pk_mul_f32 v[112:113], v[168:169], v[88:89] op_sel_hi:[1,0]
	v_pk_mul_f32 v[114:115], v[170:171], v[88:89] op_sel_hi:[1,0]
	v_pk_mul_f32 v[116:117], v[164:165], v[88:89] op_sel_hi:[1,0]
	v_pk_mul_f32 v[118:119], v[166:167], v[88:89] op_sel_hi:[1,0]
	v_pk_mul_f32 v[120:121], v[160:161], v[88:89] op_sel_hi:[1,0]
	v_pk_mul_f32 v[122:123], v[162:163], v[88:89] op_sel_hi:[1,0]
	v_pk_mul_f32 v[124:125], v[156:157], v[90:91] op_sel_hi:[1,0]
	v_pk_mul_f32 v[126:127], v[158:159], v[90:91] op_sel_hi:[1,0]
	v_pk_mul_f32 v[152:153], v[152:153], v[90:91] op_sel_hi:[1,0]
	v_pk_mul_f32 v[154:155], v[154:155], v[90:91] op_sel_hi:[1,0]
	v_pk_mul_f32 v[148:149], v[148:149], v[90:91] op_sel_hi:[1,0]
	v_pk_mul_f32 v[150:151], v[150:151], v[90:91] op_sel_hi:[1,0]
	v_pk_mul_f32 v[156:157], v[194:195], v[90:91] op_sel_hi:[1,0]
	v_pk_mul_f32 v[158:159], v[190:191], v[90:91] op_sel_hi:[1,0]
	v_pk_mul_f32 v[88:89], v[14:15], v[94:95]
	v_pk_mul_f32 v[86:87], v[12:13], v[92:93]
	v_pk_mul_f32 v[92:93], v[10:11], v[98:99]
	v_pk_mul_f32 v[90:91], v[8:9], v[96:97]
	v_pk_mul_f32 v[96:97], v[6:7], v[102:103]
	v_pk_mul_f32 v[94:95], v[4:5], v[100:101]
	v_pk_mul_f32 v[100:101], v[2:3], v[106:107]
	v_pk_mul_f32 v[98:99], v[0:1], v[104:105]
	v_pk_mul_f32 v[104:105], v[14:15], v[110:111]
	v_pk_mul_f32 v[102:103], v[12:13], v[108:109]
	v_pk_mul_f32 v[108:109], v[10:11], v[114:115]
	v_pk_mul_f32 v[106:107], v[8:9], v[112:113]
	v_pk_mul_f32 v[112:113], v[6:7], v[118:119]
	v_pk_mul_f32 v[110:111], v[4:5], v[116:117]
	v_pk_mul_f32 v[116:117], v[2:3], v[122:123]
	v_pk_mul_f32 v[114:115], v[0:1], v[120:121]
	v_pk_mul_f32 v[120:121], v[14:15], v[126:127]
	v_pk_mul_f32 v[118:119], v[12:13], v[124:125]
	v_pk_mul_f32 v[124:125], v[10:11], v[154:155]
	v_pk_mul_f32 v[122:123], v[8:9], v[152:153]
	v_pk_mul_f32 v[150:151], v[6:7], v[150:151]
	v_pk_mul_f32 v[148:149], v[4:5], v[148:149]
	v_pk_mul_f32 v[154:155], v[2:3], v[158:159]
	v_pk_mul_f32 v[152:153], v[0:1], v[156:157]
	global_store_dwordx4 v[78:79], v[86:89], off nt
	global_store_dwordx4 v[78:79], v[90:93], off offset:64 nt
	global_store_dwordx4 v[78:79], v[94:97], off offset:512 nt
	global_store_dwordx4 v[78:79], v[98:101], off offset:576 nt
	global_store_dwordx4 v[82:83], v[102:105], off nt
	global_store_dwordx4 v[82:83], v[106:109], off offset:64 nt
	global_store_dwordx4 v[82:83], v[110:113], off offset:512 nt
	global_store_dwordx4 v[82:83], v[114:117], off offset:576 nt
	global_store_dwordx4 v[178:179], v[118:121], off nt
	global_store_dwordx4 v[178:179], v[122:125], off offset:64 nt
	global_store_dwordx4 v[178:179], v[148:151], off offset:512 nt
	global_store_dwordx4 v[178:179], v[152:155], off offset:576 nt
	s_waitcnt vmcnt(15)
	v_pk_mul_f32 v[78:79], v[140:141], v[180:181] op_sel_hi:[1,0]
	v_pk_mul_f32 v[82:83], v[142:143], v[180:181] op_sel_hi:[1,0]
	v_pk_mul_f32 v[86:87], v[12:13], v[78:79]
	v_lshl_add_u64 v[78:79], s[72:73], 0, v[176:177]
	v_pk_mul_f32 v[88:89], v[14:15], v[82:83]
	v_lshl_add_u64 v[78:79], v[78:79], 0, v[74:75]
	global_store_dwordx4 v[78:79], v[86:89], off nt
	v_pk_mul_f32 v[82:83], v[136:137], v[180:181] op_sel_hi:[1,0]
	s_nop 0
	v_pk_mul_f32 v[86:87], v[138:139], v[180:181] op_sel_hi:[1,0]
	s_nop 0
	v_pk_mul_f32 v[88:89], v[10:11], v[86:87]
	v_pk_mul_f32 v[86:87], v[8:9], v[82:83]
	global_store_dwordx4 v[78:79], v[86:89], off offset:64 nt
	v_pk_mul_f32 v[82:83], v[146:147], v[180:181] op_sel_hi:[1,0]
	s_nop 0
	v_pk_mul_f32 v[86:87], v[134:135], v[180:181] op_sel_hi:[1,0]
	s_nop 0
	v_pk_mul_f32 v[88:89], v[6:7], v[86:87]
	v_pk_mul_f32 v[86:87], v[4:5], v[82:83]
	global_store_dwordx4 v[78:79], v[86:89], off offset:512 nt
	v_pk_mul_f32 v[82:83], v[188:189], v[180:181] op_sel_hi:[1,0]
	s_nop 0
	v_fmamk_f32 v88, v181, 0x3a800000, v184
	v_rsq_f32_e32 v90, v88
	v_pk_mul_f32 v[86:87], v[144:145], v[180:181] op_sel_hi:[1,0]
	v_pk_mul_f32 v[52:53], v[52:53], v[90:91] op_sel_hi:[1,0]
	v_pk_mul_f32 v[88:89], v[2:3], v[86:87]
	v_pk_mul_f32 v[86:87], v[0:1], v[82:83]
	global_store_dwordx4 v[78:79], v[86:89], off offset:576 nt
	v_lshl_add_u64 v[78:79], s[72:73], 0, v[192:193]
	v_pk_mul_f32 v[54:55], v[54:55], v[90:91] op_sel_hi:[1,0]
	v_lshl_add_u64 v[78:79], v[78:79], 0, v[74:75]
	v_pk_mul_f32 v[54:55], v[6:7], v[54:55]
	v_pk_mul_f32 v[52:53], v[4:5], v[52:53]
	global_store_dwordx4 v[78:79], v[52:55], off offset:512 nt
	v_pk_mul_f32 v[48:49], v[48:49], v[90:91] op_sel_hi:[1,0]
	v_pk_mul_f32 v[50:51], v[50:51], v[90:91] op_sel_hi:[1,0]
	s_waitcnt vmcnt(19)
	v_fmamk_f32 v52, v182, 0x3a800000, v184
	v_rsq_f32_e32 v52, v52
	v_pk_mul_f32 v[50:51], v[2:3], v[50:51]
	v_pk_mul_f32 v[48:49], v[0:1], v[48:49]
	global_store_dwordx4 v[78:79], v[48:51], off offset:576 nt
	v_pk_mul_f32 v[36:37], v[36:37], v[52:53] op_sel_hi:[1,0]
	v_pk_mul_f32 v[38:39], v[38:39], v[52:53] op_sel_hi:[1,0]
	v_lshl_add_u64 v[48:49], s[72:73], 0, v[132:133]
	v_lshl_add_u64 v[48:49], v[48:49], 0, v[74:75]
	v_pk_mul_f32 v[38:39], v[6:7], v[38:39]
	v_pk_mul_f32 v[36:37], v[4:5], v[36:37]
	global_store_dwordx4 v[48:49], v[36:39], off offset:512 nt
	v_pk_mul_f32 v[28:29], v[28:29], v[52:53] op_sel_hi:[1,0]
	v_pk_mul_f32 v[30:31], v[30:31], v[52:53] op_sel_hi:[1,0]
	s_waitcnt vmcnt(20)
	v_fmamk_f32 v36, v183, 0x3a800000, v184
	v_rsq_f32_e32 v36, v36
	v_pk_mul_f32 v[30:31], v[2:3], v[30:31]
	v_pk_mul_f32 v[28:29], v[0:1], v[28:29]
	v_pk_mul_f32 v[56:57], v[56:57], v[90:91] op_sel_hi:[1,0]
	v_pk_mul_f32 v[58:59], v[58:59], v[90:91] op_sel_hi:[1,0]
	v_pk_mul_f32 v[40:41], v[40:41], v[52:53] op_sel_hi:[1,0]
	v_pk_mul_f32 v[42:43], v[42:43], v[52:53] op_sel_hi:[1,0]
	global_store_dwordx4 v[48:49], v[28:31], off offset:576 nt
	v_pk_mul_f32 v[24:25], v[24:25], v[36:37] op_sel_hi:[1,0]
	v_pk_mul_f32 v[26:27], v[26:27], v[36:37] op_sel_hi:[1,0]
	v_pk_mul_f32 v[28:29], v[32:33], v[36:37] op_sel_hi:[1,0]
	v_lshl_add_u64 v[32:33], s[72:73], 0, v[130:131]
	v_pk_mul_f32 v[58:59], v[10:11], v[58:59]
	v_pk_mul_f32 v[56:57], v[8:9], v[56:57]
	v_pk_mul_f32 v[42:43], v[10:11], v[42:43]
	v_pk_mul_f32 v[40:41], v[8:9], v[40:41]
	v_lshl_add_u64 v[32:33], v[32:33], 0, v[74:75]
	v_pk_mul_f32 v[26:27], v[10:11], v[26:27]
	v_pk_mul_f32 v[24:25], v[8:9], v[24:25]
	global_store_dwordx4 v[78:79], v[56:59], off offset:64 nt
	global_store_dwordx4 v[48:49], v[40:43], off offset:64 nt
	global_store_dwordx4 v[32:33], v[24:27], off offset:64 nt
	v_pk_mul_f32 v[22:23], v[22:23], v[36:37] op_sel_hi:[1,0]
	s_waitcnt vmcnt(23)
	v_fmac_f32_e32 v184, 0x3a800000, v185
	v_pk_mul_f32 v[26:27], v[84:85], v[36:37] op_sel_hi:[1,0]
	v_pk_mul_f32 v[24:25], v[6:7], v[22:23]
	v_pk_mul_f32 v[22:23], v[4:5], v[26:27]
	v_rsq_f32_e32 v26, v184
	global_store_dwordx4 v[32:33], v[22:25], off offset:512 nt
	v_pk_mul_f32 v[20:21], v[20:21], v[36:37] op_sel_hi:[1,0]
	v_pk_mul_f32 v[62:63], v[62:63], v[90:91] op_sel_hi:[1,0]
	v_pk_mul_f32 v[24:25], v[80:81], v[36:37] op_sel_hi:[1,0]
	v_pk_mul_f32 v[46:47], v[46:47], v[52:53] op_sel_hi:[1,0]
	v_pk_mul_f32 v[30:31], v[34:35], v[36:37] op_sel_hi:[1,0]
	v_pk_mul_f32 v[22:23], v[2:3], v[20:21]
	v_pk_mul_f32 v[20:21], v[0:1], v[24:25]
	v_pk_mul_f32 v[18:19], v[18:19], v[26:27] op_sel_hi:[1,0]
	v_pk_mul_f32 v[60:61], v[60:61], v[90:91] op_sel_hi:[1,0]
	v_pk_mul_f32 v[62:63], v[14:15], v[62:63]
	v_pk_mul_f32 v[44:45], v[44:45], v[52:53] op_sel_hi:[1,0]
	v_pk_mul_f32 v[46:47], v[14:15], v[46:47]
	v_pk_mul_f32 v[30:31], v[14:15], v[30:31]
	global_store_dwordx4 v[32:33], v[20:23], off offset:576 nt
	v_pk_mul_f32 v[14:15], v[14:15], v[18:19]
	v_lshl_add_u64 v[18:19], s[72:73], 0, v[128:129]
	v_pk_mul_f32 v[20:21], v[76:77], v[26:27] op_sel_hi:[1,0]
	v_pk_mul_f32 v[60:61], v[12:13], v[60:61]
	v_pk_mul_f32 v[44:45], v[12:13], v[44:45]
	v_pk_mul_f32 v[28:29], v[12:13], v[28:29]
	v_pk_mul_f32 v[12:13], v[12:13], v[20:21]
	v_lshl_add_u64 v[18:19], v[18:19], 0, v[74:75]
	global_store_dwordx4 v[78:79], v[60:63], off nt
	global_store_dwordx4 v[48:49], v[44:47], off nt
	global_store_dwordx4 v[32:33], v[28:31], off nt
	global_store_dwordx4 v[18:19], v[12:15], off nt
	s_nop 1
	v_pk_mul_f32 v[12:13], v[72:73], v[26:27] op_sel_hi:[1,0]
	v_pk_mul_f32 v[14:15], v[16:17], v[26:27] op_sel_hi:[1,0]
	v_pk_mul_f32 v[8:9], v[8:9], v[12:13]
	v_pk_mul_f32 v[10:11], v[10:11], v[14:15]
	global_store_dwordx4 v[18:19], v[8:11], off offset:64 nt
	s_nop 1
	v_pk_mul_f32 v[8:9], v[68:69], v[26:27] op_sel_hi:[1,0]
	v_pk_mul_f32 v[10:11], v[70:71], v[26:27] op_sel_hi:[1,0]
	v_pk_mul_f32 v[4:5], v[4:5], v[8:9]
	v_pk_mul_f32 v[6:7], v[6:7], v[10:11]
	global_store_dwordx4 v[18:19], v[4:7], off offset:512 nt
	s_nop 1
	v_pk_mul_f32 v[4:5], v[64:65], v[26:27] op_sel_hi:[1,0]
	v_pk_mul_f32 v[6:7], v[66:67], v[26:27] op_sel_hi:[1,0]
	v_pk_mul_f32 v[0:1], v[0:1], v[4:5]
	v_pk_mul_f32 v[2:3], v[2:3], v[6:7]
	global_store_dwordx4 v[18:19], v[0:3], off offset:576 nt
